# odd attention: co-resident workgroups staggered by TG_ID parity (s_sleep 40 at phase start)
# baseline (speedup 1.0000x reference)
.LBB0_416:
	s_add_u32 s6, s2, s0
	s_addc_u32 s7, s3, s1
	global_load_dwordx4 v[2:5], v197, s[6:7] offset:256
	global_load_dwordx4 v[6:9], v197, s[6:7]
	global_load_dwordx4 v[10:13], v197, s[6:7] offset:272
	global_load_dwordx4 v[14:17], v197, s[6:7] offset:16
	s_add_u32 s6, s4, s0
	s_addc_u32 s7, s5, s1
	global_load_dwordx4 v[18:21], v197, s[6:7] offset:256
	global_load_dwordx4 v[22:25], v197, s[6:7]
	global_load_dwordx4 v[26:29], v197, s[6:7] offset:272
	global_load_dwordx4 v[30:33], v197, s[6:7] offset:16
	s_add_u32 s0, s0, 32
	s_addc_u32 s1, s1, 0
	s_cmpk_eq_i32 s0, 0x100
	s_waitcnt vmcnt(7)
	v_mov_b32_e32 v34, v2
	s_waitcnt vmcnt(6)
	v_mov_b32_e32 v35, v6
	v_mov_b32_e32 v6, v3
	v_mov_b32_e32 v2, v4
	v_mov_b32_e32 v3, v8
	v_mov_b32_e32 v8, v5
	s_waitcnt vmcnt(5)
	v_mov_b32_e32 v4, v10
	s_waitcnt vmcnt(4)
	v_mov_b32_e32 v5, v14
	v_mov_b32_e32 v14, v11
	v_mov_b32_e32 v10, v12
	v_mov_b32_e32 v11, v16
	v_mov_b32_e32 v16, v13
	s_waitcnt vmcnt(3)
	v_mov_b32_e32 v12, v18
	s_waitcnt vmcnt(2)
	v_mov_b32_e32 v13, v22
	v_mov_b32_e32 v22, v19
	v_pk_fma_f32 v[0:1], v[34:35], v[12:13], v[0:1]
	v_mov_b32_e32 v18, v20
	v_mov_b32_e32 v19, v24
	v_pk_fma_f32 v[0:1], v[6:7], v[22:23], v[0:1]
	v_mov_b32_e32 v24, v21
	v_pk_fma_f32 v[0:1], v[2:3], v[18:19], v[0:1]
	s_waitcnt vmcnt(1)
	v_mov_b32_e32 v20, v26
	s_waitcnt vmcnt(0)
	v_mov_b32_e32 v21, v30
	v_pk_fma_f32 v[0:1], v[8:9], v[24:25], v[0:1]
	v_mov_b32_e32 v30, v27
	v_pk_fma_f32 v[0:1], v[4:5], v[20:21], v[0:1]
	v_mov_b32_e32 v26, v28
	v_mov_b32_e32 v27, v32
	v_pk_fma_f32 v[0:1], v[14:15], v[30:31], v[0:1]
	v_mov_b32_e32 v32, v29
	v_pk_fma_f32 v[0:1], v[10:11], v[26:27], v[0:1]
	s_nop 0
	v_pk_fma_f32 v[0:1], v[16:17], v[32:33], v[0:1]
	s_cbranch_scc0 .LBB0_416
	v_readlane_b32 s0, v254, 46
	s_cmpk_gt_i32 s0, 0x7ff
	s_cbranch_scc1 .LBB0_436
	v_readlane_b32 s0, v254, 44
	v_mul_f32_e32 v1, 0x3fb8aa3b, v1
	v_mul_f32_e32 v0, 0x3fb8aa3b, v0
	v_cvt_f32_u32_e32 v2, s0
	v_exp_f32_e32 v1, v1
	v_exp_f32_e32 v0, v0
	v_readlane_b32 s0, v254, 52
	v_mul_f32_e32 v2, 0xbe99999a, v2
	v_mul_f32_e32 v2, 0x3fb8aa3b, v2
	v_exp_f32_e32 v2, v2
	v_readlane_b32 s1, v254, 45
	s_lshl_b32 s50, s0, 7
	v_sub_f32_e32 v0, v1, v0
	v_mov_b32_e32 v1, 0x3f4ccccd
	s_lshl_b64 s[0:1], s[50:51], 2
	v_readlane_b32 s4, v252, 1
	v_fmamk_f32 v1, v2, 0xbf19999a, v1
	v_readlane_b32 s5, v252, 2
	s_add_u32 s0, s4, s0
	v_add_f32_e32 v125, v1, v0
	v_sub_f32_e32 v127, 1.0, v1
	s_addc_u32 s1, s5, s1
	s_getreg_b32 s24, hwreg(HW_REG_HW_ID, 16, 4)
	s_and_b32 s24, s24, 1
	s_cmp_eq_u32 s24, 0
	s_cbranch_scc1 .Lstag_oa
	s_sleep 40
.Lstag_oa:
	v_readlane_b32 s24, v254, 46
	v_readlane_b32 s6, v252, 3
	v_readlane_b32 s7, v252, 4
	v_readlane_b32 s8, v252, 5
	v_readlane_b32 s9, v252, 6
	v_readlane_b32 s10, v252, 7
	v_readlane_b32 s11, v252, 8
	s_branch .LBB0_420
